# P60: RoPE table staged in 8 KB static LDS; in-projection epilogue reads cos/sin by ds_read instead of a per-row-group global load + full vmcnt wait behind the stores
# speedup vs baseline: 1.0147x; 1.0038x over previous
.LBB0_330:
	s_xor_b64 s[0:1], s[82:83], -1
	v_writelane_b32 v254, s0, 59
	s_mov_b64 s[22:23], s[88:89]
	s_mul_i32 s14, s16, 0x120000
	v_writelane_b32 v254, s1, 60
	s_and_b64 s[0:1], s[82:83], exec
	s_movk_i32 s0, 0x90
	s_cselect_b32 s13, s0, 0x80
	v_readlane_b32 s0, v254, 2
	v_readlane_b32 s1, v254, 3
	s_cselect_b32 s20, 0, 0x70
	v_writelane_b32 v254, s2, 61
	s_and_b64 s[0:1], s[0:1], s[2:3]
	s_and_b64 s[0:1], s[0:1], exec
	s_mul_i32 s21, s13, 11
	v_writelane_b32 v254, s3, 62
	s_cselect_b32 s0, 0xfffffdc0, 0
	s_cselect_b32 s51, 0x240, 0
	s_add_i32 s2, s21, s20
	s_add_i32 s0, s2, s0
	s_lshl_b32 s62, s16, 13
	s_lshl_b32 s36, s16, 3
	s_add_i32 s51, s51, s73
	s_cmp_lt_i32 s51, 2.0
	s_cselect_b64 s[4:5], -1, 0
	s_cmp_ge_i32 s51, s21
	s_cselect_b64 s[2:3], -1, 0
	v_writelane_b32 v254, s2, 63
	s_mov_b32 s15, s37
	s_mul_i32 s12, s16, 0x1800000
	v_writelane_b32 v255, s3, 0
	s_sub_i32 s2, s51, s21
	s_cmp_lt_i32 s2, s20
	s_cselect_b64 s[6:7], -1, 0
	s_ashr_i32 s3, s2, 4
	v_writelane_b32 v255, s6, 1
	s_cmp_gt_i32 s3, 2
	s_mul_i32 s1, s16, 0x2ec00
	v_writelane_b32 v255, s7, 2
	s_cselect_b32 s6, 4, 2
	s_add_i32 s6, s6, s3
	s_cmp_gt_u32 s2, 15
	s_cselect_b32 s2, s6, 0
	v_writelane_b32 v255, s2, 3
	s_ashr_i32 s2, s51, 31
	s_lshr_b32 s2, s2, 29
	s_add_i32 s2, s51, s2
	s_ashr_i32 s9, s2, 3
	s_and_b32 s6, s2, -8
	s_load_dwordx2 s[2:3], s[22:23], 0xf0
	s_lshr_b32 s18, s21, 3
	s_sub_i32 s10, s51, s6
	s_mov_b32 s6, s14
	v_writelane_b32 v255, s6, 4
	s_waitcnt lgkmcnt(0)
	s_add_u32 s19, s2, 0x5400000
	s_addc_u32 s42, s3, 0
	s_lshl_b64 s[14:15], s[14:15], 2
	v_writelane_b32 v255, s7, 5
	s_add_u32 s6, s2, s14
	v_writelane_b32 v255, s14, 6
	s_addc_u32 s7, s3, s15
	s_add_u32 s24, s6, 0x800000
	s_addc_u32 s25, s7, 0
	s_add_u32 s6, s2, s12
	s_addc_u32 s7, s3, 0
	s_add_u32 s43, s6, 0x1400000
	s_addc_u32 s46, s7, 0
	s_add_u32 s26, s2, 0x9c00000
	s_addc_u32 s27, s3, 0
	s_add_u32 s1, s2, s1
	s_addc_u32 s6, s3, 0
	s_add_u32 s47, s1, 0x200000
	s_addc_u32 s90, s6, 0
	s_add_u32 s28, s2, 0x400000
	s_addc_u32 s29, s3, 0
	v_mbcnt_lo_u32_b32 v200, -1, 0
	v_mbcnt_hi_u32_b32 v200, -1, v200
	v_lshl_add_u32 v200, s96, 6, v200
	v_lshlrev_b32_e32 v200, 4, v200
	global_load_dwordx4 v[202:205], v200, s[28:29]
	v_add_u32_e32 v200, 0x24000, v200
	s_waitcnt vmcnt(0)
	ds_write_b128 v200, v[202:205]
	s_waitcnt lgkmcnt(0)
	s_ashr_i32 s1, s0, 31
	s_abs_i32 s0, s0
	v_readlane_b32 s6, v254, 29
	s_mul_hi_u32 s6, s0, s6
	v_readlane_b32 s7, v254, 30
	s_mul_i32 s6, s6, s7
	s_sub_i32 s0, s0, s6
	s_sub_i32 s6, s0, s7
	s_cmp_ge_u32 s0, s7
	s_cselect_b32 s0, s6, s0
	s_sub_i32 s6, s0, s7
	s_cmp_ge_u32 s0, s7
	s_cselect_b32 s0, s6, s0
	v_writelane_b32 v255, s15, 7
	s_xor_b32 s0, s0, s1
	v_writelane_b32 v255, s12, 8
	s_sub_i32 s12, s0, s1
	s_cmp_lg_u32 s12, 0
	s_cselect_b64 s[0:1], -1, 0
	s_mov_b32 s6, s12
	s_cmp_le_i32 s6, s85
	s_cselect_b64 s[6:7], -1, 0
	s_and_b64 s[30:31], s[0:1], s[6:7]
	s_cmp_lt_i32 s73, s12
	s_cselect_b64 s[38:39], -1, 0
	s_add_u32 s40, s2, 0x410000
	s_addc_u32 s41, s3, 0
	s_add_u32 s0, s2, 0x500000
	s_addc_u32 s1, s3, 0
	v_writelane_b32 v255, s0, 9
	s_sub_i32 s6, s73, s12
	s_mov_b32 s11, s96
	v_writelane_b32 v255, s1, 10
	s_and_b64 s[0:1], s[30:31], exec
	s_cselect_b32 s0, s6, s91
	s_lshl_b32 s91, s0, 3
	s_sub_i32 s0, s85, s12
	v_mbcnt_lo_u32_b32 v206, -1, 0
	v_mbcnt_hi_u32_b32 v206, -1, v206
	s_add_i32 s91, s91, s11
	s_lshl_b32 s6, s0, 3
	s_and_b64 s[0:1], s[30:31], exec
	v_readlane_b32 s0, v254, 49
	s_cselect_b32 s93, s6, s0
	s_cmp_lt_i32 s91, 0x9000
	s_cselect_b64 s[60:61], -1, 0
	s_sub_i32 s0, s93, s91
	s_mul_i32 s8, s16, 0x220
	v_readlane_b32 s1, v254, 50
	s_add_i32 s0, s0, 0x8fff
	s_add_u32 s1, s2, s8
	s_addc_u32 s6, s3, 0
	s_mov_b32 s14, s16
	s_add_u32 s16, s1, 0x280000
	s_addc_u32 s17, s6, 0
	v_readlane_b32 s6, v254, 40
	v_writelane_b32 v255, s16, 11
	v_readlane_b32 s7, v254, 41
	s_lshr_b32 s1, s10, 31
	v_writelane_b32 v255, s17, 12
	s_and_b64 s[16:17], s[6:7], s[4:5]
	s_abs_i32 s4, s93
	v_cvt_f32_u32_e32 v0, s4
	s_or_b32 s1, s18, s1
	s_mul_i32 s1, s1, s10
	s_add_i32 s1, s1, s9
	v_rcp_iflag_f32_e32 v0, v0
	s_mul_hi_i32 s5, s1, 0x2e8ba2e9
	s_lshr_b32 s6, s5, 31
	s_ashr_i32 s5, s5, 4
	v_mul_f32_e32 v0, 0x4f7ffffe, v0
	v_cvt_u32_f32_e32 v0, v0
	s_sub_i32 s7, 0, s4
	s_add_i32 s5, s5, s6
	s_lshl_b32 s6, s5, 3
	v_readfirstlane_b32 s8, v0
	s_mul_i32 s7, s7, s8
	s_mulk_i32 s5, 0x58
	s_mul_hi_u32 s7, s8, s7
	s_sub_i32 s1, s1, s5
	s_abs_i32 s5, s0
	s_add_i32 s8, s8, s7
	s_mul_hi_u32 s7, s5, s8
	s_mul_i32 s8, s7, s4
	s_sub_i32 s5, s5, s8
	s_sub_i32 s8, s13, s6
	s_xor_b32 s0, s0, s93
	s_min_i32 s8, s8, 8
	s_ashr_i32 s0, s0, 31
	s_add_i32 s9, s7, 1
	s_sub_i32 s10, s5, s4
	s_cmp_ge_u32 s5, s4
	s_cselect_b32 s7, s9, s7
	s_cselect_b32 s5, s10, s5
	s_add_i32 s9, s7, 1
	s_cmp_ge_u32 s5, s4
	s_cselect_b32 s4, s9, s7
	s_abs_i32 s5, s8
	v_cvt_f32_u32_e32 v0, s5
	s_xor_b32 s4, s4, s0
	v_writelane_b32 v255, s13, 13
	s_sub_i32 s0, s4, s0
	v_rcp_iflag_f32_e32 v0, v0
	v_writelane_b32 v255, s0, 14
	s_sub_i32 s0, 0, s5
	s_mov_b32 s15, s37
	v_mul_f32_e32 v0, 0x4f7ffffe, v0
	v_cvt_u32_f32_e32 v0, v0
	v_lshl_add_u32 v207, s11, 6, v206
	s_mov_b32 s50, s62
	v_readfirstlane_b32 s4, v0
	s_mul_i32 s0, s0, s4
	s_mul_hi_u32 s0, s4, s0
	s_add_i32 s4, s4, s0
	s_abs_i32 s0, s1
	s_mul_hi_u32 s4, s0, s4
	s_mul_i32 s7, s4, s5
	s_sub_i32 s0, s0, s7
	s_xor_b32 s7, s1, s8
	s_ashr_i32 s7, s7, 31
	s_add_i32 s9, s4, 1
	s_sub_i32 s10, s0, s5
	s_cmp_ge_u32 s0, s5
	s_cselect_b32 s4, s9, s4
	s_cselect_b32 s0, s10, s0
	s_add_i32 s9, s4, 1
	s_cmp_ge_u32 s0, s5
	s_cselect_b32 s0, s9, s4
	s_xor_b32 s0, s0, s7
	s_sub_i32 s0, s0, s7
	s_mov_b32 s89, s0
	s_mul_i32 s0, s0, s8
	s_sub_i32 s0, s1, s0
	s_add_i32 s0, s6, s0
	v_writelane_b32 v255, s0, 15
	v_writelane_b32 v255, s14, 16
	s_lshl_b64 s[0:1], s[14:15], 15
	s_add_u32 s0, s40, s0
	v_writelane_b32 v255, s15, 17
	s_addc_u32 s1, s41, s1
	v_writelane_b32 v255, s0, 18
	s_mov_b64 s[6:7], -1
	s_nop 0
	v_writelane_b32 v255, s1, 19
	s_add_u32 s0, s2, 0x5400070
	s_addc_u32 s1, s3, 0
	v_writelane_b32 v255, s0, 20
	s_nop 1
	v_writelane_b32 v255, s1, 21
	v_writelane_b32 v255, s16, 22
	s_nop 1
	v_writelane_b32 v255, s17, 23
	s_branch .LBB0_334

.LBB0_479:
	s_andn2_b64 vcc, exec, s[14:15]
	s_cmp_lg_u32 s9, 0
	s_cselect_b64 s[52:53], -1, 0
	s_lshl_b64 s[10:11], s[10:11], 2
	s_add_u32 s10, s47, s10
	s_addc_u32 s11, s90, s11
	s_lshl_b32 s16, s8, 8
	s_add_i32 s16, s16, s88
	v_or_b32_e32 v200, s16, v208
	v_ashrrev_i32_e32 v201, 31, v200
	v_lshlrev_b64 v[4:5], 6, v[200:201]
	v_lshl_add_u64 v[24:25], v[184:185], 0, v[4:5]
	global_load_dwordx4 v[4:7], v[24:25], off
	v_or_b32_e32 v198, 16, v200
	v_ashrrev_i32_e32 v199, 31, v198
	v_lshlrev_b64 v[8:9], 6, v[198:199]
	v_lshl_add_u64 v[8:9], v[184:185], 0, v[8:9]
	global_load_dwordx4 v[8:11], v[8:9], off
	v_or_b32_e32 v196, 32, v200
	v_ashrrev_i32_e32 v197, 31, v196
	v_lshlrev_b64 v[12:13], 6, v[196:197]
	v_lshl_add_u64 v[12:13], v[184:185], 0, v[12:13]
	global_load_dwordx4 v[12:15], v[12:13], off
	v_or_b32_e32 v194, 48, v200
	v_ashrrev_i32_e32 v195, 31, v194
	v_lshlrev_b64 v[16:17], 6, v[194:195]
	v_lshl_add_u64 v[16:17], v[184:185], 0, v[16:17]
	global_load_dwordx4 v[16:19], v[16:17], off
	v_add_u32_e32 v192, 0x80, v200
	v_ashrrev_i32_e32 v193, 31, v192
	v_lshlrev_b64 v[20:21], 6, v[192:193]
	v_lshl_add_u64 v[20:21], v[184:185], 0, v[20:21]
	global_load_dwordx4 v[20:23], v[20:21], off
	v_add_co_u32_e32 v32, vcc, s59, v24
	v_lshl_add_u32 v190, s12, 8, v210
	s_nop 0
	v_addc_co_u32_e32 v33, vcc, 0, v25, vcc
	global_load_dwordx4 v[24:27], v[32:33], off offset:1024
	global_load_dwordx4 v[28:31], v[32:33], off offset:2048
	global_load_dwordx4 v[66:69], v[32:33], off offset:3072
	v_ashrrev_i32_e32 v191, 31, v190
	v_lshl_add_u64 v[2:3], v[190:191], 2, s[10:11]
	s_and_b64 s[10:11], s[6:7], s[52:53]
	s_andn2_b64 vcc, exec, s[10:11]
	s_waitcnt vmcnt(0)
	v_add_f32_e32 v4, v4, v5
	v_add_f32_e32 v5, v6, v7
	v_add_f32_e32 v4, v4, v5
	ds_swizzle_b32 v5, v4 offset:swizzle(SWAP,16)
	s_waitcnt lgkmcnt(0)
	v_add_f32_e32 v197, v4, v5
	v_add_f32_e32 v4, v8, v9
	v_add_f32_e32 v5, v10, v11
	v_add_f32_e32 v4, v4, v5
	ds_swizzle_b32 v5, v4 offset:swizzle(SWAP,16)
	v_mov_b32_e32 v202, v197
	s_nop 1
	v_permlane32_swap_b32_e32 v197, v202
	s_waitcnt lgkmcnt(0)
	v_add_f32_e32 v224, v4, v5
	v_add_f32_e32 v4, v12, v13
	v_add_f32_e32 v5, v14, v15
	v_add_f32_e32 v4, v4, v5
	ds_swizzle_b32 v5, v4 offset:swizzle(SWAP,16)
	v_mov_b32_e32 v225, v224
	s_nop 1
	v_permlane32_swap_b32_e32 v224, v225
	s_waitcnt lgkmcnt(0)
	v_add_f32_e32 v222, v4, v5
	v_add_f32_e32 v4, v16, v17
	v_add_f32_e32 v5, v18, v19
	v_add_f32_e32 v4, v4, v5
	ds_swizzle_b32 v5, v4 offset:swizzle(SWAP,16)
	v_mov_b32_e32 v223, v222
	s_nop 1
	v_permlane32_swap_b32_e32 v222, v223
	s_waitcnt lgkmcnt(0)
	v_add_f32_e32 v220, v4, v5
	v_add_f32_e32 v4, v20, v21
	v_add_f32_e32 v5, v22, v23
	v_add_f32_e32 v4, v4, v5
	ds_swizzle_b32 v5, v4 offset:swizzle(SWAP,16)
	v_mov_b32_e32 v221, v220
	s_nop 1
	v_permlane32_swap_b32_e32 v220, v221
	s_waitcnt lgkmcnt(0)
	v_add_f32_e32 v218, v4, v5
	v_add_f32_e32 v4, v24, v25
	v_add_f32_e32 v5, v26, v27
	v_add_f32_e32 v4, v4, v5
	ds_swizzle_b32 v5, v4 offset:swizzle(SWAP,16)
	v_mov_b32_e32 v219, v218
	s_nop 1
	v_permlane32_swap_b32_e32 v218, v219
	s_waitcnt lgkmcnt(0)
	v_add_f32_e32 v216, v4, v5
	v_add_f32_e32 v4, v28, v29
	v_add_f32_e32 v5, v30, v31
	v_add_f32_e32 v4, v4, v5
	ds_swizzle_b32 v5, v4 offset:swizzle(SWAP,16)
	v_mov_b32_e32 v217, v216
	s_nop 1
	v_permlane32_swap_b32_e32 v216, v217
	s_waitcnt lgkmcnt(0)
	v_add_f32_e32 v199, v4, v5
	v_add_f32_e32 v4, v66, v67
	v_add_f32_e32 v5, v68, v69
	global_load_dwordx4 v[82:85], v[2:3], off offset:16
	global_load_dwordx4 v[86:89], v[2:3], off
	global_load_dwordx4 v[66:69], v[2:3], off offset:528
	global_load_dwordx4 v[70:73], v[2:3], off offset:512
	v_add_f32_e32 v4, v4, v5
	ds_swizzle_b32 v5, v4 offset:swizzle(SWAP,16)
	v_mov_b32_e32 v201, v199
	v_cndmask_b32_e64 v2, 0, 1, s[10:11]
	s_nop 0
	v_permlane32_swap_b32_e32 v199, v201
	s_waitcnt lgkmcnt(0)
	v_add_f32_e32 v193, v4, v5
	v_mov_b32_e32 v195, v193
	s_nop 1
	v_permlane32_swap_b32_e32 v193, v195
	v_cmp_ne_u32_e64 s[14:15], 1, v2
	s_cbranch_vccnz .LBB0_481
	s_bfe_u32 s8, s16, 0x50006
	v_mov_b32_e32 v2, s8
	v_cndmask_b32_e64 v2, v208, v2, s[2:3]
	v_lshlrev_b32_e32 v3, 2, v211
	v_lshl_or_b32 v2, v2, 7, v3
	v_add_u32_e32 v206, 0x24000, v2
	ds_read_b128 v[14:17], v206 offset:48
	ds_read_b128 v[10:13], v206 offset:32
	ds_read_b128 v[6:9], v206 offset:16
	s_nop 0
	ds_read_b128 v[2:5], v206
.LBB0_481:
	s_and_b64 vcc, exec, s[14:15]
	v_mov_b32_e32 v18, 0
	s_cbranch_vccnz .LBB0_483
	s_bfe_u32 s8, s16, 0x50006
	v_mov_b32_e32 v18, s8
	v_cndmask_b32_e64 v18, v212, v18, s[2:3]
	v_lshlrev_b32_e32 v19, 2, v211
	v_lshl_or_b32 v18, v18, 7, v19
	v_add_u32_e32 v206, 0x24000, v18
	ds_read_b128 v[226:229], v206
	ds_read_b128 v[230:233], v206 offset:16
	ds_read_b128 v[234:237], v206 offset:32
	ds_read_b128 v[238:241], v206 offset:48
	s_waitcnt lgkmcnt(4)
	v_mov_b32_e32 v18, v2
	v_mov_b32_e32 v19, v3
	v_mov_b32_e32 v20, v4
	v_mov_b32_e32 v21, v5
	v_mov_b32_e32 v22, v6
	v_mov_b32_e32 v23, v7
	v_mov_b32_e32 v24, v8
	v_mov_b32_e32 v25, v9
	v_mov_b32_e32 v26, v10
	v_mov_b32_e32 v27, v11
	v_mov_b32_e32 v28, v12
	v_mov_b32_e32 v29, v13
	v_mov_b32_e32 v30, v14
	v_mov_b32_e32 v31, v15
	v_mov_b32_e32 v32, v16
	v_mov_b32_e32 v33, v17
	s_waitcnt lgkmcnt(3)
	v_mov_b64_e32 v[2:3], v[226:227]
	s_waitcnt lgkmcnt(2)
	v_mov_b64_e32 v[6:7], v[230:231]
	s_waitcnt lgkmcnt(1)
	v_mov_b64_e32 v[10:11], v[234:235]
	s_waitcnt lgkmcnt(0)
	v_mov_b64_e32 v[14:15], v[238:239]
	v_mov_b64_e32 v[4:5], v[228:229]
	v_mov_b64_e32 v[8:9], v[232:233]
	v_mov_b64_e32 v[12:13], v[236:237]
	v_mov_b64_e32 v[16:17], v[240:241]
	s_branch .LBB0_484

.LBB0_492:
	v_cvt_pk_bf16_f32 v166, v166, v167
	v_cvt_pk_bf16_f32 v167, v168, v169
	v_cvt_pk_bf16_f32 v168, v162, v163
	s_nop 0
	v_cvt_pk_bf16_f32 v169, v164, v165
	global_store_dwordx4 v[170:171], v[166:169], off offset:256
	s_and_b64 vcc, exec, s[14:15]
	s_cbranch_vccnz .LBB0_494
	s_bfe_u32 s17, s16, 0x50006
	v_mov_b32_e32 v18, s17
	v_cndmask_b32_e64 v18, v213, v18, s[2:3]
	v_lshlrev_b32_e32 v19, 2, v211
	v_lshl_or_b32 v18, v18, 7, v19
	v_add_u32_e32 v206, 0x24000, v18
	ds_read_b128 v[162:165], v206
	ds_read_b128 v[226:229], v206 offset:16
	ds_read_b128 v[230:233], v206 offset:32
	ds_read_b128 v[234:237], v206 offset:48
	v_mov_b64_e32 v[32:33], v[16:17]
	v_mov_b32_e32 v166, v2
	v_mov_b32_e32 v169, v3
	v_mov_b32_e32 v167, v4
	v_mov_b32_e32 v171, v5
	v_mov_b32_e32 v168, v6
	v_mov_b32_e32 v173, v7
	v_mov_b32_e32 v170, v8
	v_mov_b32_e32 v175, v9
	v_mov_b32_e32 v172, v10
	v_mov_b32_e32 v177, v11
	v_mov_b32_e32 v174, v12
	v_mov_b32_e32 v202, v13
	v_mov_b32_e32 v176, v14
	v_mov_b32_e32 v203, v15
	v_mov_b32_e32 v200, v16
	v_mov_b32_e32 v204, v17
	v_mov_b64_e32 v[30:31], v[14:15]
	v_mov_b64_e32 v[28:29], v[12:13]
	v_mov_b64_e32 v[26:27], v[10:11]
	v_mov_b64_e32 v[24:25], v[8:9]
	v_mov_b64_e32 v[22:23], v[6:7]
	v_mov_b64_e32 v[20:21], v[4:5]
	v_mov_b64_e32 v[18:19], v[2:3]
	s_waitcnt lgkmcnt(3)
	v_mov_b64_e32 v[2:3], v[162:163]
	s_waitcnt lgkmcnt(2)
	v_mov_b64_e32 v[6:7], v[226:227]
	s_waitcnt lgkmcnt(1)
	v_mov_b64_e32 v[10:11], v[230:231]
	s_waitcnt lgkmcnt(0)
	v_mov_b64_e32 v[14:15], v[234:235]
	v_mov_b64_e32 v[4:5], v[164:165]
	v_mov_b64_e32 v[8:9], v[228:229]
	v_mov_b64_e32 v[12:13], v[232:233]
	v_mov_b64_e32 v[16:17], v[236:237]
	s_branch .LBB0_495

.LBB0_503:
	v_cvt_pk_bf16_f32 v150, v150, v151
	v_cvt_pk_bf16_f32 v151, v152, v153
	v_cvt_pk_bf16_f32 v152, v146, v147
	s_nop 0
	v_cvt_pk_bf16_f32 v153, v148, v149
	global_store_dwordx4 v[154:155], v[150:153], off offset:256
	s_and_b64 vcc, exec, s[14:15]
	s_cbranch_vccnz .LBB0_505
	s_bfe_u32 s16, s16, 0x50006
	v_mov_b32_e32 v18, s16
	v_cndmask_b32_e64 v18, v214, v18, s[2:3]
	v_lshlrev_b32_e32 v19, 2, v211
	v_lshl_or_b32 v18, v18, 7, v19
	v_add_u32_e32 v206, 0x24000, v18
	ds_read_b128 v[146:149], v206
	ds_read_b128 v[150:153], v206 offset:16
	ds_read_b128 v[154:157], v206 offset:32
	ds_read_b128 v[158:161], v206 offset:48
	v_mov_b64_e32 v[32:33], v[16:17]
	v_mov_b32_e32 v166, v2
	v_mov_b32_e32 v169, v3
	v_mov_b32_e32 v167, v4
	v_mov_b32_e32 v171, v5
	v_mov_b32_e32 v168, v6
	v_mov_b32_e32 v173, v7
	v_mov_b32_e32 v170, v8
	v_mov_b32_e32 v175, v9
	v_mov_b32_e32 v172, v10
	v_mov_b32_e32 v177, v11
	v_mov_b32_e32 v174, v12
	v_mov_b32_e32 v202, v13
	v_mov_b32_e32 v176, v14
	v_mov_b32_e32 v203, v15
	v_mov_b32_e32 v200, v16
	v_mov_b32_e32 v204, v17
	v_mov_b64_e32 v[30:31], v[14:15]
	v_mov_b64_e32 v[28:29], v[12:13]
	v_mov_b64_e32 v[26:27], v[10:11]
	v_mov_b64_e32 v[24:25], v[8:9]
	v_mov_b64_e32 v[22:23], v[6:7]
	v_mov_b64_e32 v[20:21], v[4:5]
	v_mov_b64_e32 v[18:19], v[2:3]
	s_waitcnt lgkmcnt(3)
	v_mov_b64_e32 v[2:3], v[146:147]
	s_waitcnt lgkmcnt(2)
	v_mov_b64_e32 v[6:7], v[150:151]
	s_waitcnt lgkmcnt(1)
	v_mov_b64_e32 v[10:11], v[154:155]
	s_waitcnt lgkmcnt(0)
	v_mov_b64_e32 v[14:15], v[158:159]
	v_mov_b64_e32 v[4:5], v[148:149]
	v_mov_b64_e32 v[8:9], v[152:153]
	v_mov_b64_e32 v[12:13], v[156:157]
	v_mov_b64_e32 v[16:17], v[160:161]

.LBB0_513:
	v_cvt_pk_bf16_f32 v134, v134, v135
	v_cvt_pk_bf16_f32 v135, v136, v137
	v_cvt_pk_bf16_f32 v136, v130, v131
	s_nop 0
	v_cvt_pk_bf16_f32 v137, v132, v133
	global_store_dwordx4 v[138:139], v[134:137], off offset:256
	s_and_b64 vcc, exec, s[14:15]
	s_cbranch_vccnz .LBB0_515
	v_bfe_u32 v18, v192, 6, 5
	v_cndmask_b32_e64 v18, v208, v18, s[2:3]
	v_lshlrev_b32_e32 v19, 2, v211
	v_lshl_or_b32 v18, v18, 7, v19
	v_add_u32_e32 v206, 0x24000, v18
	ds_read_b128 v[130:133], v206
	ds_read_b128 v[134:137], v206 offset:16
	ds_read_b128 v[138:141], v206 offset:32
	ds_read_b128 v[142:145], v206 offset:48
	v_mov_b64_e32 v[32:33], v[16:17]
	v_mov_b32_e32 v166, v2
	v_mov_b32_e32 v169, v3
	v_mov_b32_e32 v167, v4
	v_mov_b32_e32 v171, v5
	v_mov_b32_e32 v168, v6
	v_mov_b32_e32 v173, v7
	v_mov_b32_e32 v170, v8
	v_mov_b32_e32 v175, v9
	v_mov_b32_e32 v172, v10
	v_mov_b32_e32 v177, v11
	v_mov_b32_e32 v174, v12
	v_mov_b32_e32 v202, v13
	v_mov_b32_e32 v176, v14
	v_mov_b32_e32 v203, v15
	v_mov_b32_e32 v200, v16
	v_mov_b32_e32 v204, v17
	v_mov_b64_e32 v[30:31], v[14:15]
	v_mov_b64_e32 v[28:29], v[12:13]
	v_mov_b64_e32 v[26:27], v[10:11]
	v_mov_b64_e32 v[24:25], v[8:9]
	v_mov_b64_e32 v[22:23], v[6:7]
	v_mov_b64_e32 v[20:21], v[4:5]
	v_mov_b64_e32 v[18:19], v[2:3]
	s_waitcnt lgkmcnt(3)
	v_mov_b64_e32 v[2:3], v[130:131]
	s_waitcnt lgkmcnt(2)
	v_mov_b64_e32 v[6:7], v[134:135]
	s_waitcnt lgkmcnt(1)
	v_mov_b64_e32 v[10:11], v[138:139]
	s_waitcnt lgkmcnt(0)
	v_mov_b64_e32 v[14:15], v[142:143]
	v_mov_b64_e32 v[4:5], v[132:133]
	v_mov_b64_e32 v[8:9], v[136:137]
	v_mov_b64_e32 v[12:13], v[140:141]
	v_mov_b64_e32 v[16:17], v[144:145]

.LBB0_523:
	v_cvt_pk_bf16_f32 v118, v118, v119
	v_cvt_pk_bf16_f32 v119, v120, v121
	v_cvt_pk_bf16_f32 v120, v114, v115
	s_nop 0
	v_cvt_pk_bf16_f32 v121, v116, v117
	global_store_dwordx4 v[122:123], v[118:121], off offset:256
	s_and_b64 vcc, exec, s[14:15]
	s_cbranch_vccnz .LBB0_525
	v_bfe_u32 v18, v192, 6, 5
	v_cndmask_b32_e64 v18, v212, v18, s[2:3]
	v_lshlrev_b32_e32 v19, 2, v211
	v_lshl_or_b32 v18, v18, 7, v19
	v_add_u32_e32 v206, 0x24000, v18
	ds_read_b128 v[114:117], v206
	ds_read_b128 v[118:121], v206 offset:16
	ds_read_b128 v[122:125], v206 offset:32
	ds_read_b128 v[126:129], v206 offset:48
	v_mov_b64_e32 v[32:33], v[16:17]
	v_mov_b32_e32 v166, v2
	v_mov_b32_e32 v169, v3
	v_mov_b32_e32 v167, v4
	v_mov_b32_e32 v171, v5
	v_mov_b32_e32 v168, v6
	v_mov_b32_e32 v173, v7
	v_mov_b32_e32 v170, v8
	v_mov_b32_e32 v175, v9
	v_mov_b32_e32 v172, v10
	v_mov_b32_e32 v177, v11
	v_mov_b32_e32 v174, v12
	v_mov_b32_e32 v202, v13
	v_mov_b32_e32 v176, v14
	v_mov_b32_e32 v203, v15
	v_mov_b32_e32 v200, v16
	v_mov_b32_e32 v204, v17
	v_mov_b64_e32 v[30:31], v[14:15]
	v_mov_b64_e32 v[28:29], v[12:13]
	v_mov_b64_e32 v[26:27], v[10:11]
	v_mov_b64_e32 v[24:25], v[8:9]
	v_mov_b64_e32 v[22:23], v[6:7]
	v_mov_b64_e32 v[20:21], v[4:5]
	v_mov_b64_e32 v[18:19], v[2:3]
	s_waitcnt lgkmcnt(3)
	v_mov_b64_e32 v[2:3], v[114:115]
	s_waitcnt lgkmcnt(2)
	v_mov_b64_e32 v[6:7], v[118:119]
	s_waitcnt lgkmcnt(1)
	v_mov_b64_e32 v[10:11], v[122:123]
	s_waitcnt lgkmcnt(0)
	v_mov_b64_e32 v[14:15], v[126:127]
	v_mov_b64_e32 v[4:5], v[116:117]
	v_mov_b64_e32 v[8:9], v[120:121]
	v_mov_b64_e32 v[12:13], v[124:125]
	v_mov_b64_e32 v[16:17], v[128:129]

.LBB0_533:
	v_cvt_pk_bf16_f32 v102, v102, v103
	v_cvt_pk_bf16_f32 v103, v104, v105
	v_cvt_pk_bf16_f32 v104, v98, v99
	s_nop 0
	v_cvt_pk_bf16_f32 v105, v100, v101
	global_store_dwordx4 v[106:107], v[102:105], off offset:256
	s_and_b64 vcc, exec, s[14:15]
	s_cbranch_vccnz .LBB0_535
	v_bfe_u32 v18, v192, 6, 5
	v_cndmask_b32_e64 v18, v213, v18, s[2:3]
	v_lshlrev_b32_e32 v19, 2, v211
	v_lshl_or_b32 v18, v18, 7, v19
	v_add_u32_e32 v206, 0x24000, v18
	ds_read_b128 v[98:101], v206
	ds_read_b128 v[102:105], v206 offset:16
	ds_read_b128 v[106:109], v206 offset:32
	ds_read_b128 v[110:113], v206 offset:48
	v_mov_b64_e32 v[32:33], v[16:17]
	v_mov_b32_e32 v166, v2
	v_mov_b32_e32 v169, v3
	v_mov_b32_e32 v167, v4
	v_mov_b32_e32 v171, v5
	v_mov_b32_e32 v168, v6
	v_mov_b32_e32 v173, v7
	v_mov_b32_e32 v170, v8
	v_mov_b32_e32 v175, v9
	v_mov_b32_e32 v172, v10
	v_mov_b32_e32 v177, v11
	v_mov_b32_e32 v174, v12
	v_mov_b32_e32 v202, v13
	v_mov_b32_e32 v176, v14
	v_mov_b32_e32 v203, v15
	v_mov_b32_e32 v200, v16
	v_mov_b32_e32 v204, v17
	v_mov_b64_e32 v[30:31], v[14:15]
	v_mov_b64_e32 v[28:29], v[12:13]
	v_mov_b64_e32 v[26:27], v[10:11]
	v_mov_b64_e32 v[24:25], v[8:9]
	v_mov_b64_e32 v[22:23], v[6:7]
	v_mov_b64_e32 v[20:21], v[4:5]
	v_mov_b64_e32 v[18:19], v[2:3]
	s_waitcnt lgkmcnt(3)
	v_mov_b64_e32 v[2:3], v[98:99]
	s_waitcnt lgkmcnt(2)
	v_mov_b64_e32 v[6:7], v[102:103]
	s_waitcnt lgkmcnt(1)
	v_mov_b64_e32 v[10:11], v[106:107]
	s_waitcnt lgkmcnt(0)
	v_mov_b64_e32 v[14:15], v[110:111]
	v_mov_b64_e32 v[4:5], v[100:101]
	v_mov_b64_e32 v[8:9], v[104:105]
	v_mov_b64_e32 v[12:13], v[108:109]
	v_mov_b64_e32 v[16:17], v[112:113]

.LBB0_543:
	v_cvt_pk_bf16_f32 v78, v78, v79
	v_cvt_pk_bf16_f32 v79, v80, v81
	v_cvt_pk_bf16_f32 v80, v74, v75
	s_nop 0
	v_cvt_pk_bf16_f32 v81, v76, v77
	global_store_dwordx4 v[90:91], v[78:81], off offset:256
	s_and_b64 vcc, exec, s[14:15]
	s_cbranch_vccnz .LBB0_545
	v_bfe_u32 v18, v192, 6, 5
	v_cndmask_b32_e64 v18, v214, v18, s[2:3]
	v_lshlrev_b32_e32 v19, 2, v211
	v_lshl_or_b32 v18, v18, 7, v19
	v_add_u32_e32 v206, 0x24000, v18
	ds_read_b128 v[74:77], v206
	ds_read_b128 v[78:81], v206 offset:16
	ds_read_b128 v[90:93], v206 offset:32
	ds_read_b128 v[94:97], v206 offset:48
	v_mov_b64_e32 v[32:33], v[16:17]
	v_mov_b32_e32 v166, v2
	v_mov_b32_e32 v169, v3
	v_mov_b32_e32 v167, v4
	v_mov_b32_e32 v171, v5
	v_mov_b32_e32 v168, v6
	v_mov_b32_e32 v173, v7
	v_mov_b32_e32 v170, v8
	v_mov_b32_e32 v175, v9
	v_mov_b32_e32 v172, v10
	v_mov_b32_e32 v177, v11
	v_mov_b32_e32 v174, v12
	v_mov_b32_e32 v202, v13
	v_mov_b32_e32 v176, v14
	v_mov_b32_e32 v203, v15
	v_mov_b32_e32 v200, v16
	v_mov_b32_e32 v204, v17
	v_mov_b64_e32 v[30:31], v[14:15]
	v_mov_b64_e32 v[28:29], v[12:13]
	v_mov_b64_e32 v[26:27], v[10:11]
	v_mov_b64_e32 v[24:25], v[8:9]
	v_mov_b64_e32 v[22:23], v[6:7]
	v_mov_b64_e32 v[20:21], v[4:5]
	v_mov_b64_e32 v[18:19], v[2:3]
	s_waitcnt lgkmcnt(3)
	v_mov_b64_e32 v[2:3], v[74:75]
	s_waitcnt lgkmcnt(2)
	v_mov_b64_e32 v[6:7], v[78:79]
	s_waitcnt lgkmcnt(1)
	v_mov_b64_e32 v[10:11], v[90:91]
	s_waitcnt lgkmcnt(0)
	v_mov_b64_e32 v[14:15], v[94:95]
	v_mov_b64_e32 v[4:5], v[76:77]
	v_mov_b64_e32 v[8:9], v[80:81]
	v_mov_b64_e32 v[12:13], v[92:93]
	v_mov_b64_e32 v[16:17], v[96:97]

	.amdhsa_kernel _Z10hybrid_fwd4Args
		.amdhsa_group_segment_fixed_size 8192
		.amdhsa_private_segment_fixed_size 0
		.amdhsa_kernarg_size 504
		.amdhsa_user_sgpr_count 2
		.amdhsa_user_sgpr_dispatch_ptr 0
		.amdhsa_user_sgpr_queue_ptr 0
		.amdhsa_user_sgpr_kernarg_segment_ptr 1
		.amdhsa_user_sgpr_dispatch_id 0
		.amdhsa_user_sgpr_kernarg_preload_length 0
		.amdhsa_user_sgpr_kernarg_preload_offset 0
		.amdhsa_user_sgpr_private_segment_size 0
		.amdhsa_uses_dynamic_stack 0
		.amdhsa_enable_private_segment 0
		.amdhsa_system_sgpr_workgroup_id_x 1
		.amdhsa_system_sgpr_workgroup_id_y 0
		.amdhsa_system_sgpr_workgroup_id_z 0
		.amdhsa_system_sgpr_workgroup_info 0
		.amdhsa_system_vgpr_workitem_id 2
		.amdhsa_next_free_vgpr 256
		.amdhsa_next_free_sgpr 102
		.amdhsa_accum_offset 256
		.amdhsa_reserve_vcc 1
		.amdhsa_float_round_mode_32 0
		.amdhsa_float_round_mode_16_64 0
		.amdhsa_float_denorm_mode_32 3
		.amdhsa_float_denorm_mode_16_64 3
		.amdhsa_dx10_clamp 1
		.amdhsa_ieee_mode 1
		.amdhsa_fp16_overflow 0
		.amdhsa_tg_split 0
		.amdhsa_exception_fp_ieee_invalid_op 0
		.amdhsa_exception_fp_denorm_src 0
		.amdhsa_exception_fp_ieee_div_zero 0
		.amdhsa_exception_fp_ieee_overflow 0
		.amdhsa_exception_fp_ieee_underflow 0
		.amdhsa_exception_fp_ieee_inexact 0
		.amdhsa_exception_int_div_zero 0
	.end_amdhsa_kernel

amdhsa.kernels:
  - .agpr_count:     0
    .args:
      - .offset:         0
        .size:           248
        .value_kind:     by_value
      - .offset:         248
        .size:           4
        .value_kind:     hidden_block_count_x
      - .offset:         252
        .size:           4
        .value_kind:     hidden_block_count_y
      - .offset:         256
        .size:           4
        .value_kind:     hidden_block_count_z
      - .offset:         260
        .size:           2
        .value_kind:     hidden_group_size_x
      - .offset:         262
        .size:           2
        .value_kind:     hidden_group_size_y
      - .offset:         264
        .size:           2
        .value_kind:     hidden_group_size_z
      - .offset:         266
        .size:           2
        .value_kind:     hidden_remainder_x
      - .offset:         268
        .size:           2
        .value_kind:     hidden_remainder_y
      - .offset:         270
        .size:           2
        .value_kind:     hidden_remainder_z
      - .offset:         288
        .size:           8
        .value_kind:     hidden_global_offset_x
      - .offset:         296
        .size:           8
        .value_kind:     hidden_global_offset_y
      - .offset:         304
        .size:           8
        .value_kind:     hidden_global_offset_z
      - .offset:         312
        .size:           2
        .value_kind:     hidden_grid_dims
      - .offset:         336
        .size:           8
        .value_kind:     hidden_multigrid_sync_arg
      - .offset:         368
        .size:           4
        .value_kind:     hidden_dynamic_lds_size
    .group_segment_fixed_size: 8192
    .kernarg_segment_align: 8
    .kernarg_segment_size: 504
    .language:       OpenCL C
    .language_version:
      - 2
      - 0
    .max_flat_workgroup_size: 512
    .name:           _Z10hybrid_fwd4Args
    .private_segment_fixed_size: 0
    .sgpr_count:     108
    .sgpr_spill_count: 124
    .symbol:         _Z10hybrid_fwd4Args.kd
    .uniform_work_group_size: 1
    .uses_dynamic_stack: false
    .vgpr_count:     256
    .vgpr_spill_count: 0
    .wavefront_size: 64
